# gdn prompt scan: compute-wave chunk body hand-scheduled with LDS fragment prefetch (6 buffers), decay factor prefetched one chunk ahead
# speedup vs baseline: 1.0127x; 1.0127x over previous
; DI void gdn_scan_prompt(const Params& p, int bh, unsigned char* smem) {
;     ...
;             LAS unsigned char* base = lds + (n & 1) * 73728 + lane * 16;
;             const float dl = *(const float*)(gblk + (size_t)n * GOP_STRIDE + 73728);
;             bf16x8 Ub[4];
;             {
;                 f32x16 U[2];
; #pragma unroll
;                 for (int rt = 0; rt < 2; ++rt) {
; #pragma unroll
;                     for (int g = 0; g < 2; ++g) { const u32x4 v = *(const LAS u32x4*)(lds + (n & 1) * 73728 + 57344 + (((s * 2 + rt) * 64 + lane) << 5) + 16 * g);
;                         U[rt][8 * g] = bflo(v.x); U[rt][8 * g + 1] = bfhi(v.x); U[rt][8 * g + 2] = bflo(v.y); U[rt][8 * g + 3] = bfhi(v.y);
;                         U[rt][8 * g + 4] = bflo(v.z); U[rt][8 * g + 5] = bfhi(v.z); U[rt][8 * g + 6] = bflo(v.w); U[rt][8 * g + 7] = bfhi(v.w); }
;                 }
; #pragma unroll
;                 for (int t = 0; t < 4; ++t)
; #pragma unroll
;                     for (int s2 = 0; s2 < 2; ++s2) {
;                         const bf16x8 sb = packB(S[t], s2);
; #pragma unroll
;                         for (int rt = 0; rt < 2; ++rt) U[rt] = MFMA32(LDSV((rt * 8 + 2 * t + s2) * 1024), sb, U[rt]);
;                     }
; #pragma unroll
;                 for (int kc = 0; kc < 4; ++kc) Ub[kc] = packB(U[kc >> 1], kc & 1);
;             }
;             f32x16 O[2];
; #pragma unroll
;             for (int rt = 0; rt < 2; ++rt)
; #pragma unroll
;                 for (int i = 0; i < 16; ++i) O[rt][i] = 0.f;
; #pragma unroll
;             for (int t = 0; t < 4; ++t)
; #pragma unroll
;                 for (int s2 = 0; s2 < 2; ++s2) {
;                     const bf16x8 sb = packB(S[t], s2);
; #pragma unroll
;                     for (int rt = 0; rt < 2; ++rt) O[rt] = MFMA32(LDSV(16384 + (rt * 8 + 2 * t + s2) * 1024), sb, O[rt]);
;                 }
; #pragma unroll
;             for (int rt = 0; rt < 2; ++rt)
; #pragma unroll
;                 for (int kc = 0; kc < 2 * rt + 2; ++kc) O[rt] = MFMA32(LDSV(49152 + (rt * 4 + kc) * 1024), Ub[kc], O[rt]);
;             const size_t tok0 = (size_t)b * 2048 + n * 64;
; #pragma unroll
;             for (int rt = 0; rt < 2; ++rt)
; #pragma unroll
;                 for (int i = 0; i < 16; ++i) oraw[(tok0 + 32 * rt + crow(i, hh)) * 1024 + h * 128 + 32 * s + l31] = f2bf(O[rt][i]);
; #pragma unroll
;             for (int t = 0; t < 4; ++t) {
.LBB0_844:
	v_cndmask_b32_e64 v2, 0, 1, s[26:27]
	v_cmp_ne_u32_e64 s[0:1], 1, v2
	s_andn2_b64 vcc, exec, s[26:27]
	s_cbranch_vccnz .LBB0_847
	s_bitcmp1_b32 s7, 0
	s_cselect_b32 s25, 0x12000, 0
	s_add_u32 s90, s83, s58
	s_addc_u32 s91, s33, s59
	s_add_i32 s35, s25, s13
	v_add_u32_e32 v92, s35, v196
	v_add_u32_e32 v197, s25, v194
	s_cmp_lg_u32 s7, 0
	s_cbranch_scc1 .Lgs_dl_have
	global_load_dword v244, v192, s[90:91]
	s_waitcnt vmcnt(0)
.Lgs_dl_have:
	v_add_u32_e32 v246, 0x12100, v192
	ds_read_b128 v[72:75], v92 offset:57344
	ds_read_b128 v[80:83], v92 offset:57360
	ds_read_b128 v[88:91], v92 offset:59392
	ds_read_b128 v[96:99], v92 offset:59408
	global_load_dword v245, v246, s[90:91]
	ds_read_b128 v[222:225], v197
	ds_read_b128 v[226:229], v197 offset:8192
	ds_read_b128 v[230:233], v197 offset:1024
	ds_read_b128 v[234:237], v197 offset:9216
	ds_read_b128 v[148:151], v197 offset:2048
	ds_read_b128 v[240:243], v197 offset:10240
	v_cvt_pk_bf16_f32 v116, v52, v53
	v_cvt_pk_bf16_f32 v117, v54, v55
	v_cvt_pk_bf16_f32 v118, v56, v57
	v_cvt_pk_bf16_f32 v119, v58, v59
	v_cvt_pk_bf16_f32 v120, v60, v61
	v_cvt_pk_bf16_f32 v121, v62, v63
	v_cvt_pk_bf16_f32 v122, v64, v65
	v_cvt_pk_bf16_f32 v123, v66, v67
	s_waitcnt lgkmcnt(8)
	v_lshlrev_b32_e32 v68, 16, v72
	v_and_b32_e32 v69, 0xffff0000, v72
	v_lshlrev_b32_e32 v70, 16, v73
	v_and_b32_e32 v71, 0xffff0000, v73
	v_lshlrev_b32_e32 v72, 16, v74
	v_and_b32_e32 v73, 0xffff0000, v74
	v_lshlrev_b32_e32 v74, 16, v75
	v_and_b32_e32 v75, 0xffff0000, v75
	v_lshlrev_b32_e32 v76, 16, v80
	v_and_b32_e32 v77, 0xffff0000, v80
	v_lshlrev_b32_e32 v78, 16, v81
	v_and_b32_e32 v79, 0xffff0000, v81
	v_lshlrev_b32_e32 v80, 16, v82
	v_and_b32_e32 v81, 0xffff0000, v82
	v_lshlrev_b32_e32 v82, 16, v83
	v_and_b32_e32 v83, 0xffff0000, v83
	s_waitcnt lgkmcnt(6)
	v_lshlrev_b32_e32 v84, 16, v88
	v_and_b32_e32 v85, 0xffff0000, v88
	v_lshlrev_b32_e32 v86, 16, v89
	v_and_b32_e32 v87, 0xffff0000, v89
	v_lshlrev_b32_e32 v88, 16, v90
	v_and_b32_e32 v89, 0xffff0000, v90
	v_lshlrev_b32_e32 v90, 16, v91
	v_and_b32_e32 v91, 0xffff0000, v91
	v_lshlrev_b32_e32 v92, 16, v96
	v_and_b32_e32 v93, 0xffff0000, v96
	v_lshlrev_b32_e32 v94, 16, v97
	v_and_b32_e32 v95, 0xffff0000, v97
	v_lshlrev_b32_e32 v96, 16, v98
	v_and_b32_e32 v97, 0xffff0000, v98
	v_lshlrev_b32_e32 v98, 16, v99
	v_and_b32_e32 v99, 0xffff0000, v99
	s_waitcnt lgkmcnt(5)
	v_mfma_f32_32x32x16_bf16 v[68:83], v[222:225], v[116:119], v[68:83]
	ds_read_b128 v[222:225], v197 offset:3072
	v_cvt_pk_bf16_f32 v124, v36, v37
	v_cvt_pk_bf16_f32 v125, v38, v39
	s_waitcnt lgkmcnt(5)
	v_mfma_f32_32x32x16_bf16 v[84:99], v[226:229], v[116:119], v[84:99]
	ds_read_b128 v[226:229], v197 offset:11264
	v_cvt_pk_bf16_f32 v126, v40, v41
	v_cvt_pk_bf16_f32 v127, v42, v43
	s_waitcnt lgkmcnt(5)
	v_mfma_f32_32x32x16_bf16 v[68:83], v[230:233], v[120:123], v[68:83]
	ds_read_b128 v[230:233], v197 offset:4096
	v_cvt_pk_bf16_f32 v128, v44, v45
	v_cvt_pk_bf16_f32 v129, v46, v47
	s_waitcnt lgkmcnt(5)
	v_mfma_f32_32x32x16_bf16 v[84:99], v[234:237], v[120:123], v[84:99]
	ds_read_b128 v[234:237], v197 offset:12288
	v_cvt_pk_bf16_f32 v130, v48, v49
	v_cvt_pk_bf16_f32 v131, v50, v51
	s_waitcnt lgkmcnt(5)
	v_mfma_f32_32x32x16_bf16 v[68:83], v[148:151], v[124:127], v[68:83]
	ds_read_b128 v[148:151], v197 offset:5120
	v_cvt_pk_bf16_f32 v132, v20, v21
	v_cvt_pk_bf16_f32 v133, v22, v23
	s_waitcnt lgkmcnt(5)
	v_mfma_f32_32x32x16_bf16 v[84:99], v[240:243], v[124:127], v[84:99]
	ds_read_b128 v[240:243], v197 offset:13312
	v_cvt_pk_bf16_f32 v134, v24, v25
	v_cvt_pk_bf16_f32 v135, v26, v27
	s_waitcnt lgkmcnt(5)
	v_mfma_f32_32x32x16_bf16 v[68:83], v[222:225], v[128:131], v[68:83]
	ds_read_b128 v[222:225], v197 offset:6144
	v_cvt_pk_bf16_f32 v136, v28, v29
	v_cvt_pk_bf16_f32 v137, v30, v31
	s_waitcnt lgkmcnt(5)
	v_mfma_f32_32x32x16_bf16 v[84:99], v[226:229], v[128:131], v[84:99]
	ds_read_b128 v[226:229], v197 offset:14336
	v_cvt_pk_bf16_f32 v138, v32, v33
	v_cvt_pk_bf16_f32 v139, v34, v35
	s_waitcnt lgkmcnt(5)
	v_mfma_f32_32x32x16_bf16 v[68:83], v[230:233], v[132:135], v[68:83]
	ds_read_b128 v[230:233], v197 offset:7168
	v_cvt_pk_bf16_f32 v140, v4, v5
	v_cvt_pk_bf16_f32 v141, v6, v7
	s_waitcnt lgkmcnt(5)
	v_mfma_f32_32x32x16_bf16 v[84:99], v[234:237], v[132:135], v[84:99]
	ds_read_b128 v[234:237], v197 offset:15360
	v_cvt_pk_bf16_f32 v142, v8, v9
	v_cvt_pk_bf16_f32 v143, v10, v11
	s_waitcnt lgkmcnt(5)
	v_mfma_f32_32x32x16_bf16 v[68:83], v[148:151], v[136:139], v[68:83]
	ds_read_b128 v[148:151], v197 offset:16384
	v_cvt_pk_bf16_f32 v144, v12, v13
	v_cvt_pk_bf16_f32 v145, v14, v15
	s_waitcnt lgkmcnt(5)
	v_mfma_f32_32x32x16_bf16 v[84:99], v[240:243], v[136:139], v[84:99]
	ds_read_b128 v[240:243], v197 offset:24576
	v_cvt_pk_bf16_f32 v146, v16, v17
	v_cvt_pk_bf16_f32 v147, v18, v19
	s_waitcnt lgkmcnt(5)
	v_mfma_f32_32x32x16_bf16 v[68:83], v[222:225], v[140:143], v[68:83]
	ds_read_b128 v[222:225], v197 offset:17408
	s_waitcnt lgkmcnt(5)
	v_mfma_f32_32x32x16_bf16 v[84:99], v[226:229], v[140:143], v[84:99]
	ds_read_b128 v[226:229], v197 offset:25600
	s_waitcnt lgkmcnt(5)
	v_mfma_f32_32x32x16_bf16 v[68:83], v[230:233], v[144:147], v[68:83]
	ds_read_b128 v[230:233], v197 offset:18432
	s_waitcnt lgkmcnt(5)
	v_mfma_f32_32x32x16_bf16 v[84:99], v[234:237], v[144:147], v[84:99]
	ds_read_b128 v[234:237], v197 offset:26624
	s_waitcnt lgkmcnt(5)
	v_mfma_f32_32x32x16_bf16 v[156:171], v[148:151], v[116:119], 0
	ds_read_b128 v[148:151], v197 offset:19456
	v_mul_f32_e32 v52, v244, v52
	v_mul_f32_e32 v53, v244, v53
	v_mul_f32_e32 v54, v244, v54
	v_mul_f32_e32 v55, v244, v55
	s_waitcnt lgkmcnt(5)
; DI bf16_t f2bf(float a) { return (bf16_t)(pk_bf16(a, 0.f) & 0xffffu); }
; #define MFMA32(a, b, c) __builtin_amdgcn_mfma_f32_32x32x16_bf16((a), (b), (c), 0, 0, 0)
; DI int crow(int i, int hh) { return (i & 3) + 8 * (i >> 2) + 4 * hh; }
; DI void gdn_scan_prompt(const Params& p, int bh, unsigned char* smem) {
;     ...
;                 for (int kc = 0; kc < 4; ++kc) Ub[kc] = packB(U[kc >> 1], kc & 1);
;             }
;             f32x16 O[2];
; #pragma unroll
;             for (int rt = 0; rt < 2; ++rt)
; #pragma unroll
;                 for (int i = 0; i < 16; ++i) O[rt][i] = 0.f;
; #pragma unroll
;             for (int t = 0; t < 4; ++t)
; #pragma unroll
;                 for (int s2 = 0; s2 < 2; ++s2) {
;                     const bf16x8 sb = packB(S[t], s2);
; #pragma unroll
;                     for (int rt = 0; rt < 2; ++rt) O[rt] = MFMA32(LDSV(16384 + (rt * 8 + 2 * t + s2) * 1024), sb, O[rt]);
;                 }
; #pragma unroll
;             for (int rt = 0; rt < 2; ++rt)
; #pragma unroll
;                 for (int kc = 0; kc < 2 * rt + 2; ++kc) O[rt] = MFMA32(LDSV(49152 + (rt * 4 + kc) * 1024), Ub[kc], O[rt]);
;             const size_t tok0 = (size_t)b * 2048 + n * 64;
; #pragma unroll
;             for (int rt = 0; rt < 2; ++rt)
; #pragma unroll
;                 for (int i = 0; i < 16; ++i) oraw[(tok0 + 32 * rt + crow(i, hh)) * 1024 + h * 128 + 32 * s + l31] = f2bf(O[rt][i]);
; #pragma unroll
;             for (int t = 0; t < 4; ++t) {
; #pragma unroll
;                 for (int i = 0; i < 16; ++i) S[t][i] *= dl;
; #pragma unroll
;                 for (int kc = 0; kc < 4; ++kc) S[t] = MFMA32(LDSV(32768 + (t * 4 + kc) * 1024), Ub[kc], S[t]);
	v_mfma_f32_32x32x16_bf16 v[172:187], v[240:243], v[116:119], 0
	ds_read_b128 v[240:243], v197 offset:27648
	v_mul_f32_e32 v56, v244, v56
	v_mul_f32_e32 v57, v244, v57
	v_mul_f32_e32 v58, v244, v58
	v_mul_f32_e32 v59, v244, v59
	s_waitcnt lgkmcnt(5)
	v_mfma_f32_32x32x16_bf16 v[156:171], v[222:225], v[120:123], v[156:171]
	ds_read_b128 v[222:225], v197 offset:20480
	v_mul_f32_e32 v60, v244, v60
	v_mul_f32_e32 v61, v244, v61
	v_mul_f32_e32 v62, v244, v62
	v_mul_f32_e32 v63, v244, v63
	s_waitcnt lgkmcnt(5)
	v_mfma_f32_32x32x16_bf16 v[172:187], v[226:229], v[120:123], v[172:187]
	ds_read_b128 v[226:229], v197 offset:28672
	v_mul_f32_e32 v64, v244, v64
	v_mul_f32_e32 v65, v244, v65
	v_mul_f32_e32 v66, v244, v66
	v_mul_f32_e32 v67, v244, v67
	s_waitcnt lgkmcnt(5)
	v_mfma_f32_32x32x16_bf16 v[156:171], v[230:233], v[124:127], v[156:171]
	ds_read_b128 v[230:233], v197 offset:21504
	v_mul_f32_e32 v36, v244, v36
	v_mul_f32_e32 v37, v244, v37
	v_mul_f32_e32 v38, v244, v38
	v_mul_f32_e32 v39, v244, v39
	v_cvt_pk_bf16_f32 v112, v68, v69
	v_cvt_pk_bf16_f32 v113, v70, v71
	s_waitcnt lgkmcnt(5)
	v_mfma_f32_32x32x16_bf16 v[172:187], v[234:237], v[124:127], v[172:187]
	ds_read_b128 v[234:237], v197 offset:29696
	v_mul_f32_e32 v40, v244, v40
	v_mul_f32_e32 v41, v244, v41
	v_mul_f32_e32 v42, v244, v42
	v_mul_f32_e32 v43, v244, v43
	v_cvt_pk_bf16_f32 v114, v72, v73
	v_cvt_pk_bf16_f32 v115, v74, v75
	s_waitcnt lgkmcnt(5)
	v_mfma_f32_32x32x16_bf16 v[156:171], v[148:151], v[128:131], v[156:171]
	ds_read_b128 v[148:151], v197 offset:22528
	v_mul_f32_e32 v44, v244, v44
	v_mul_f32_e32 v45, v244, v45
	v_mul_f32_e32 v46, v244, v46
	v_mul_f32_e32 v47, v244, v47
	v_cvt_pk_bf16_f32 v108, v76, v77
	v_cvt_pk_bf16_f32 v109, v78, v79
	s_waitcnt lgkmcnt(5)
	v_mfma_f32_32x32x16_bf16 v[172:187], v[240:243], v[128:131], v[172:187]
	ds_read_b128 v[240:243], v197 offset:30720
	v_mul_f32_e32 v48, v244, v48
	v_mul_f32_e32 v49, v244, v49
	v_mul_f32_e32 v50, v244, v50
	v_mul_f32_e32 v51, v244, v51
	v_cvt_pk_bf16_f32 v110, v80, v81
	v_cvt_pk_bf16_f32 v111, v82, v83
	s_waitcnt lgkmcnt(5)
	v_mfma_f32_32x32x16_bf16 v[156:171], v[222:225], v[132:135], v[156:171]
	ds_read_b128 v[222:225], v197 offset:23552
	v_mul_f32_e32 v20, v244, v20
	v_mul_f32_e32 v21, v244, v21
	v_mul_f32_e32 v22, v244, v22
	v_mul_f32_e32 v23, v244, v23
	v_cvt_pk_bf16_f32 v104, v84, v85
	v_cvt_pk_bf16_f32 v105, v86, v87
	s_waitcnt lgkmcnt(5)
	v_mfma_f32_32x32x16_bf16 v[172:187], v[226:229], v[132:135], v[172:187]
	ds_read_b128 v[226:229], v197 offset:31744
	v_mul_f32_e32 v24, v244, v24
	v_mul_f32_e32 v25, v244, v25
	v_mul_f32_e32 v26, v244, v26
	v_mul_f32_e32 v27, v244, v27
	v_cvt_pk_bf16_f32 v106, v88, v89
	v_cvt_pk_bf16_f32 v107, v90, v91
	s_waitcnt lgkmcnt(5)
	v_mfma_f32_32x32x16_bf16 v[156:171], v[230:233], v[136:139], v[156:171]
	ds_read_b128 v[230:233], v197 offset:49152
	v_mul_f32_e32 v28, v244, v28
	v_mul_f32_e32 v29, v244, v29
	v_mul_f32_e32 v30, v244, v30
	v_mul_f32_e32 v31, v244, v31
	v_cvt_pk_bf16_f32 v100, v92, v93
	v_cvt_pk_bf16_f32 v101, v94, v95
	s_waitcnt lgkmcnt(5)
	v_mfma_f32_32x32x16_bf16 v[172:187], v[234:237], v[136:139], v[172:187]
	ds_read_b128 v[234:237], v197 offset:53248
	v_mul_f32_e32 v32, v244, v32
	v_mul_f32_e32 v33, v244, v33
	v_mul_f32_e32 v34, v244, v34
	v_mul_f32_e32 v35, v244, v35
	v_cvt_pk_bf16_f32 v102, v96, v97
	v_cvt_pk_bf16_f32 v103, v98, v99
	s_waitcnt lgkmcnt(5)
	v_mfma_f32_32x32x16_bf16 v[156:171], v[148:151], v[140:143], v[156:171]
	ds_read_b128 v[148:151], v197 offset:50176
	v_mul_f32_e32 v4, v244, v4
	v_mul_f32_e32 v5, v244, v5
	v_mul_f32_e32 v6, v244, v6
	v_mul_f32_e32 v7, v244, v7
	s_waitcnt lgkmcnt(5)
	v_mfma_f32_32x32x16_bf16 v[172:187], v[240:243], v[140:143], v[172:187]
	ds_read_b128 v[240:243], v197 offset:54272
	v_mul_f32_e32 v8, v244, v8
	v_mul_f32_e32 v9, v244, v9
	v_mul_f32_e32 v10, v244, v10
	v_mul_f32_e32 v11, v244, v11
	s_waitcnt lgkmcnt(5)
	v_mfma_f32_32x32x16_bf16 v[156:171], v[222:225], v[144:147], v[156:171]
	ds_read_b128 v[222:225], v197 offset:55296
	v_mul_f32_e32 v12, v244, v12
	v_mul_f32_e32 v13, v244, v13
	v_mul_f32_e32 v14, v244, v14
	v_mul_f32_e32 v15, v244, v15
	s_waitcnt lgkmcnt(5)
	v_mfma_f32_32x32x16_bf16 v[172:187], v[226:229], v[144:147], v[172:187]
	ds_read_b128 v[226:229], v197 offset:56320
	v_mul_f32_e32 v16, v244, v16
	v_mul_f32_e32 v17, v244, v17
	v_mul_f32_e32 v18, v244, v18
	v_mul_f32_e32 v19, v244, v19
	s_waitcnt lgkmcnt(5)
	v_mfma_f32_32x32x16_bf16 v[156:171], v[230:233], v[112:115], v[156:171]
	ds_read_b128 v[230:233], v197 offset:32768
	v_lshl_add_u64 v[250:251], s[78:79], 0, v[190:191]
	s_waitcnt lgkmcnt(5)
	v_mfma_f32_32x32x16_bf16 v[172:187], v[234:237], v[112:115], v[172:187]
	ds_read_b128 v[234:237], v197 offset:33792
	v_add_co_u32_e32 v68, vcc, 0x1000, v250
	s_waitcnt lgkmcnt(5)
	v_mfma_f32_32x32x16_bf16 v[156:171], v[148:151], v[108:111], v[156:171]
	ds_read_b128 v[148:151], v197 offset:34816
	v_addc_co_u32_e32 v69, vcc, 0, v251, vcc
	v_add_co_u32_e32 v70, vcc, 0x5000, v250
	s_waitcnt lgkmcnt(5)
	v_mfma_f32_32x32x16_bf16 v[172:187], v[240:243], v[108:111], v[172:187]
	ds_read_b128 v[240:243], v197 offset:35840
	v_addc_co_u32_e32 v71, vcc, 0, v251, vcc
	v_add_co_u32_e32 v72, vcc, 0x9000, v250
	s_waitcnt lgkmcnt(5)
	v_mfma_f32_32x32x16_bf16 v[172:187], v[222:225], v[104:107], v[172:187]
	ds_read_b128 v[222:225], v197 offset:36864
	v_addc_co_u32_e32 v73, vcc, 0, v251, vcc
	v_add_co_u32_e32 v74, vcc, 0xd000, v250
	s_waitcnt lgkmcnt(5)
; DI bf16_t f2bf(float a) { return (bf16_t)(pk_bf16(a, 0.f) & 0xffffu); }
; #define MFMA32(a, b, c) __builtin_amdgcn_mfma_f32_32x32x16_bf16((a), (b), (c), 0, 0, 0)
; DI int crow(int i, int hh) { return (i & 3) + 8 * (i >> 2) + 4 * hh; }
; DI void gdn_scan_prompt(const Params& p, int bh, unsigned char* smem) {
;     ...
;             const size_t tok0 = (size_t)b * 2048 + n * 64;
; #pragma unroll
;             for (int rt = 0; rt < 2; ++rt)
; #pragma unroll
;                 for (int i = 0; i < 16; ++i) oraw[(tok0 + 32 * rt + crow(i, hh)) * 1024 + h * 128 + 32 * s + l31] = f2bf(O[rt][i]);
; #pragma unroll
;             for (int t = 0; t < 4; ++t) {
; #pragma unroll
;                 for (int i = 0; i < 16; ++i) S[t][i] *= dl;
; #pragma unroll
;                 for (int kc = 0; kc < 4; ++kc) S[t] = MFMA32(LDSV(32768 + (t * 4 + kc) * 1024), Ub[kc], S[t]);
;             }
	v_mfma_f32_32x32x16_bf16 v[172:187], v[226:229], v[100:103], v[172:187]
	ds_read_b128 v[226:229], v197 offset:37888
	v_addc_co_u32_e32 v75, vcc, 0, v251, vcc
	v_add_co_u32_e32 v76, vcc, 0x11000, v250
	s_waitcnt lgkmcnt(5)
	v_mfma_f32_32x32x16_bf16 v[52:67], v[230:233], v[112:115], v[52:67]
	ds_read_b128 v[230:233], v197 offset:38912
	v_addc_co_u32_e32 v77, vcc, 0, v251, vcc
	v_add_co_u32_e32 v78, vcc, 0x15000, v250
	s_waitcnt lgkmcnt(5)
	v_mfma_f32_32x32x16_bf16 v[52:67], v[234:237], v[108:111], v[52:67]
	ds_read_b128 v[234:237], v197 offset:39936
	v_addc_co_u32_e32 v79, vcc, 0, v251, vcc
	v_add_co_u32_e32 v80, vcc, 0x19000, v250
	v_cvt_pk_bf16_f32 v247, v156, v156
	global_store_short v[68:69], v247, off offset:-4096
	v_cvt_pk_bf16_f32 v248, v157, v157
	global_store_short v[68:69], v248, off offset:-2048
	s_waitcnt lgkmcnt(5)
	v_mfma_f32_32x32x16_bf16 v[52:67], v[148:151], v[104:107], v[52:67]
	ds_read_b128 v[148:151], v197 offset:40960
	v_addc_co_u32_e32 v81, vcc, 0, v251, vcc
	v_add_co_u32_e32 v82, vcc, 0x1d000, v250
	v_cvt_pk_bf16_f32 v247, v158, v158
	global_store_short v[68:69], v247, off
	v_cvt_pk_bf16_f32 v248, v159, v159
	global_store_short v[68:69], v248, off offset:2048
	s_waitcnt lgkmcnt(5)
	v_mfma_f32_32x32x16_bf16 v[52:67], v[240:243], v[100:103], v[52:67]
	ds_read_b128 v[240:243], v197 offset:41984
	v_addc_co_u32_e32 v83, vcc, 0, v251, vcc
	v_cvt_pk_bf16_f32 v247, v160, v160
	global_store_short v[70:71], v247, off offset:-4096
	v_cvt_pk_bf16_f32 v248, v161, v161
	global_store_short v[70:71], v248, off offset:-2048
	s_waitcnt lgkmcnt(5)
	v_mfma_f32_32x32x16_bf16 v[36:51], v[222:225], v[112:115], v[36:51]
	ds_read_b128 v[222:225], v197 offset:43008
	v_cvt_pk_bf16_f32 v247, v162, v162
	global_store_short v[70:71], v247, off
	v_cvt_pk_bf16_f32 v248, v163, v163
	global_store_short v[70:71], v248, off offset:2048
	s_waitcnt lgkmcnt(5)
	v_mfma_f32_32x32x16_bf16 v[36:51], v[226:229], v[108:111], v[36:51]
	ds_read_b128 v[226:229], v197 offset:44032
	v_cvt_pk_bf16_f32 v247, v164, v164
	global_store_short v[72:73], v247, off offset:-4096
	v_cvt_pk_bf16_f32 v248, v165, v165
	global_store_short v[72:73], v248, off offset:-2048
	s_waitcnt lgkmcnt(5)
	v_mfma_f32_32x32x16_bf16 v[36:51], v[230:233], v[104:107], v[36:51]
	ds_read_b128 v[230:233], v197 offset:45056
	v_cvt_pk_bf16_f32 v247, v166, v166
	global_store_short v[72:73], v247, off
	v_cvt_pk_bf16_f32 v248, v167, v167
	global_store_short v[72:73], v248, off offset:2048
	s_waitcnt lgkmcnt(5)
	v_mfma_f32_32x32x16_bf16 v[36:51], v[234:237], v[100:103], v[36:51]
	ds_read_b128 v[234:237], v197 offset:46080
	v_cvt_pk_bf16_f32 v247, v168, v168
	global_store_short v[74:75], v247, off offset:-4096
	v_cvt_pk_bf16_f32 v248, v169, v169
	global_store_short v[74:75], v248, off offset:-2048
	s_waitcnt lgkmcnt(5)
	v_mfma_f32_32x32x16_bf16 v[20:35], v[148:151], v[112:115], v[20:35]
	ds_read_b128 v[148:151], v197 offset:47104
	v_cvt_pk_bf16_f32 v247, v170, v170
	global_store_short v[74:75], v247, off
	v_cvt_pk_bf16_f32 v248, v171, v171
	global_store_short v[74:75], v248, off offset:2048
	v_cvt_pk_bf16_f32 v247, v172, v172
	global_store_short v[76:77], v247, off offset:-4096
	v_cvt_pk_bf16_f32 v248, v173, v173
	global_store_short v[76:77], v248, off offset:-2048
	s_waitcnt lgkmcnt(5)
	v_mfma_f32_32x32x16_bf16 v[20:35], v[240:243], v[108:111], v[20:35]
	ds_read_b128 v[240:243], v197 offset:48128
	v_cvt_pk_bf16_f32 v247, v174, v174
	global_store_short v[76:77], v247, off
	v_cvt_pk_bf16_f32 v248, v175, v175
	global_store_short v[76:77], v248, off offset:2048
	s_waitcnt lgkmcnt(5)
	v_mfma_f32_32x32x16_bf16 v[20:35], v[222:225], v[104:107], v[20:35]
	v_cvt_pk_bf16_f32 v247, v176, v176
	global_store_short v[78:79], v247, off offset:-4096
	v_cvt_pk_bf16_f32 v248, v177, v177
	global_store_short v[78:79], v248, off offset:-2048
	s_waitcnt lgkmcnt(4)
	v_mfma_f32_32x32x16_bf16 v[20:35], v[226:229], v[100:103], v[20:35]
	v_cvt_pk_bf16_f32 v247, v178, v178
	global_store_short v[78:79], v247, off
	v_cvt_pk_bf16_f32 v248, v179, v179
	global_store_short v[78:79], v248, off offset:2048
	s_waitcnt lgkmcnt(3)
	v_mfma_f32_32x32x16_bf16 v[4:19], v[230:233], v[112:115], v[4:19]
	v_cvt_pk_bf16_f32 v247, v180, v180
	global_store_short v[80:81], v247, off offset:-4096
	v_cvt_pk_bf16_f32 v248, v181, v181
	global_store_short v[80:81], v248, off offset:-2048
	s_waitcnt lgkmcnt(2)
	v_mfma_f32_32x32x16_bf16 v[4:19], v[234:237], v[108:111], v[4:19]
	v_cvt_pk_bf16_f32 v247, v182, v182
	global_store_short v[80:81], v247, off
	v_cvt_pk_bf16_f32 v248, v183, v183
	global_store_short v[80:81], v248, off offset:2048
	s_waitcnt lgkmcnt(1)
	v_mfma_f32_32x32x16_bf16 v[4:19], v[148:151], v[104:107], v[4:19]
	v_cvt_pk_bf16_f32 v247, v184, v184
	global_store_short v[82:83], v247, off offset:-4096
	v_cvt_pk_bf16_f32 v248, v185, v185
	global_store_short v[82:83], v248, off offset:-2048
	s_waitcnt lgkmcnt(0)
	v_mfma_f32_32x32x16_bf16 v[4:19], v[240:243], v[100:103], v[4:19]
	v_cvt_pk_bf16_f32 v247, v186, v186
	global_store_short v[82:83], v247, off
	v_cvt_pk_bf16_f32 v248, v187, v187
	global_store_short v[82:83], v248, off offset:2048
	s_nop 0
	s_waitcnt vmcnt(32)
	v_mov_b32_e32 v244, v245
	s_mov_b64 s[90:91], -1
	s_and_b64 vcc, exec, s[22:23]
	s_cbranch_vccnz .LBB0_848

; __global__ void __launch_bounds__(512) hybrid_fwd(Params p) {
	.amdhsa_kernel _Z10hybrid_fwd6Params
		.amdhsa_group_segment_fixed_size 0
		.amdhsa_private_segment_fixed_size 0
		.amdhsa_kernarg_size 416
		.amdhsa_user_sgpr_count 2
		.amdhsa_user_sgpr_dispatch_ptr 0
		.amdhsa_user_sgpr_queue_ptr 0
		.amdhsa_user_sgpr_kernarg_segment_ptr 1
		.amdhsa_user_sgpr_dispatch_id 0
		.amdhsa_user_sgpr_kernarg_preload_length 0
		.amdhsa_user_sgpr_kernarg_preload_offset 0
		.amdhsa_user_sgpr_private_segment_size 0
		.amdhsa_uses_dynamic_stack 0
		.amdhsa_enable_private_segment 0
		.amdhsa_system_sgpr_workgroup_id_x 1
		.amdhsa_system_sgpr_workgroup_id_y 0
		.amdhsa_system_sgpr_workgroup_id_z 0
		.amdhsa_system_sgpr_workgroup_info 0
		.amdhsa_system_vgpr_workitem_id 2
		.amdhsa_next_free_vgpr 256
		.amdhsa_next_free_sgpr 98
		.amdhsa_accum_offset 256
		.amdhsa_reserve_vcc 1
		.amdhsa_float_round_mode_32 0
		.amdhsa_float_round_mode_16_64 0
		.amdhsa_float_denorm_mode_32 3
		.amdhsa_float_denorm_mode_16_64 3
		.amdhsa_dx10_clamp 1
		.amdhsa_ieee_mode 1
		.amdhsa_fp16_overflow 0
		.amdhsa_tg_split 0
		.amdhsa_exception_fp_ieee_invalid_op 0
		.amdhsa_exception_fp_denorm_src 0
		.amdhsa_exception_fp_ieee_div_zero 0
		.amdhsa_exception_fp_ieee_overflow 0
		.amdhsa_exception_fp_ieee_underflow 0
		.amdhsa_exception_fp_ieee_inexact 0
		.amdhsa_exception_int_div_zero 0
	.end_amdhsa_kernel

; __global__ void __launch_bounds__(512) hybrid_fwd(Params p) {
amdhsa.kernels:
  - .agpr_count:     0
    .args:
      - .offset:         0
        .size:           160
        .value_kind:     by_value
      - .offset:         160
        .size:           4
        .value_kind:     hidden_block_count_x
      - .offset:         164
        .size:           4
        .value_kind:     hidden_block_count_y
      - .offset:         168
        .size:           4
        .value_kind:     hidden_block_count_z
      - .offset:         172
        .size:           2
        .value_kind:     hidden_group_size_x
      - .offset:         174
        .size:           2
        .value_kind:     hidden_group_size_y
      - .offset:         176
        .size:           2
        .value_kind:     hidden_group_size_z
      - .offset:         178
        .size:           2
        .value_kind:     hidden_remainder_x
      - .offset:         180
        .size:           2
        .value_kind:     hidden_remainder_y
      - .offset:         182
        .size:           2
        .value_kind:     hidden_remainder_z
      - .offset:         200
        .size:           8
        .value_kind:     hidden_global_offset_x
      - .offset:         208
        .size:           8
        .value_kind:     hidden_global_offset_y
      - .offset:         216
        .size:           8
        .value_kind:     hidden_global_offset_z
      - .offset:         224
        .size:           2
        .value_kind:     hidden_grid_dims
      - .offset:         248
        .size:           8
        .value_kind:     hidden_multigrid_sync_arg
      - .offset:         280
        .size:           4
        .value_kind:     hidden_dynamic_lds_size
    .group_segment_fixed_size: 0
    .kernarg_segment_align: 8
    .kernarg_segment_size: 416
    .language:       OpenCL C
    .language_version:
      - 2
      - 0
    .max_flat_workgroup_size: 512
    .name:           _Z10hybrid_fwd6Params
    .private_segment_fixed_size: 0
    .sgpr_count:     104
    .sgpr_spill_count: 37
    .symbol:         _Z10hybrid_fwd6Params.kd
    .uniform_work_group_size: 1
    .uses_dynamic_stack: false
    .vgpr_count:     256
    .vgpr_spill_count: 0
    .wavefront_size: 64
